# speedup vs baseline: 1.0112x; 1.0112x over previous
; template <int K, int EPI>
; __device__ __forceinline__ void gemm_all(const u16* A, const u16* Bt, int nN, u16* Cb, int ldc, const float* R, float* Cf) {
;     ...
;   for (int t = blockIdx.x; t < nW * 256; t += gridDim.x) {
;     const int w = t >> 8, r = t & 255, x = r & 7, i = r >> 3;
;     const int pm = x * 4 + (i & 3), pn = w * 8 + (i >> 2);
;     ...
;     if (pn < nN) gemm_tile<K, EPI>(A, Bt, pm * BM, pn * BM, Cb, ldc, R, Cf);
.LBB0_816:
	s_or_b64 exec, exec, s[62:63]
	s_cmpk_eq_i32 s46, 0x100
	s_cbranch_scc0 .Lp3b_generic
	s_cmpk_lt_u32 s24, 0x80
	s_cbranch_scc1 .LBB0_1079
	s_cmp_eq_u32 s72, s24
	s_cbranch_scc1 .Lp3b_second
	s_add_i32 s2, s24, 0x100
	s_cmp_eq_u32 s72, s2
	s_cbranch_scc0 .LBB0_1079
	s_add_i32 s72, s24, 0x80
	s_branch .Lp3b_go
.Lp3b_second:
	s_add_i32 s72, s24, 0x100
.Lp3b_go:
	s_lshl_b32 s33, s72, 2
	s_branch .LBB0_817
.Lp3b_generic:
	s_add_i32 s72, s72, s46
	s_add_i32 s33, s33, s47
	s_cmpk_lt_i32 s72, 0x200
	s_cbranch_scc0 .LBB0_1079

; __device__ __forceinline__ void diff_combine(const Params& p) {
;     ...
;   for (int u = gw; u < T_TOK * 8; u += nw) {
;     const int tok = u >> 3, h = u & 7;
;     const uint2 a = na, b = nb_, gq = ng;
;     const int un = u + nw;
;     if (un < T_TOK * 8) {
;       const int tokn = un >> 3, hn = un & 7;
;       const u16* o0 = ob + (size_t)tokn * 4096 + (hn * 2) * 256 + lane * 4;
;       na = *(const uint2*)o0; nb_ = *(const uint2*)(o0 + 256);
;       ng = *(const uint2*)(proj + (size_t)tokn * NEP + E_GB + hn * 256 + lane * 4);
;     }
.Ldc_entry:
	v_add_u32_e32 v254, s28, v14
	v_mov_b32_e32 v31, v254
	v_cmp_gt_i32_e64 s[2:3], s23, v31
	s_and_saveexec_b64 s[18:19], s[2:3]
	s_cbranch_execz .Ldc_preskip
	v_ashrrev_i32_e32 v248, 3, v31
	v_ashrrev_i32_e32 v249, 31, v248
	v_mov_b64_e32 v[252:253], s[42:43]
	v_lshlrev_b64 v[250:251], 13, v[248:249]
	v_mad_i64_i32 v[248:249], s[36:37], v248, s38, v[252:253]
	v_mov_b32_e32 v11, v7
	v_lshl_add_u64 v[248:249], v[248:249], 0, v[10:11]
	v_lshl_add_u64 v[248:249], v[4:5], 1, v[248:249]
	v_lshl_add_u64 v[250:251], v[12:13], 0, v[250:251]
	v_add_co_u32_e32 v252, vcc, 0x4000, v248
	s_nop 1
	v_addc_co_u32_e32 v253, vcc, 0, v249, vcc
	global_load_dwordx2 v[242:243], v[250:251], off
	global_load_dwordx2 v[244:245], v[250:251], off offset:512
	s_nop 0
	global_load_dwordx2 v[246:247], v[252:253], off offset:3200

; __device__ __forceinline__ float silu(float g) { return g * __builtin_amdgcn_rcpf(1.f + __expf(-g)); }
; __device__ __forceinline__ void diff_combine(const Params& p) {
;     ...
;   for (int u = gw; u < T_TOK * 8; u += nw) {
;     const int tok = u >> 3, h = u & 7;
;     const uint2 a = na, b = nb_, gq = ng;
;     const int un = u + nw;
;     if (un < T_TOK * 8) {
;       const int tokn = un >> 3, hn = un & 7;
;       const u16* o0 = ob + (size_t)tokn * 4096 + (hn * 2) * 256 + lane * 4;
;       na = *(const uint2*)o0; nb_ = *(const uint2*)(o0 + 256);
;       ng = *(const uint2*)(proj + (size_t)tokn * NEP + E_GB + hn * 256 + lane * 4);
;     }
;     __builtin_amdgcn_sched_barrier(0);
;     float o[4];
;     o[0] = __uint_as_float(a.x << 16) - lam * __uint_as_float(b.x << 16);
;     o[1] = __uint_as_float(a.x & 0xffff0000u) - lam * __uint_as_float(b.x & 0xffff0000u);
;     o[2] = __uint_as_float(a.y << 16) - lam * __uint_as_float(b.y << 16);
;     o[3] = __uint_as_float(a.y & 0xffff0000u) - lam * __uint_as_float(b.y & 0xffff0000u);
;     float ss = o[0] * o[0] + o[1] * o[1] + o[2] * o[2] + o[3] * o[3];
;     ss = wave_sum(ss);
;     const float rs = rsqrtf(ss * (1.f / 256.f) + EPS) * (1.f - lambda_init);
;     const float g0 = __uint_as_float(gq.x << 16), g1 = __uint_as_float(gq.x & 0xffff0000u), g2 = __uint_as_float(gq.y << 16), g3 = __uint_as_float(gq.y & 0xffff0000u);
;     const float y0 = o[0] * rs * sg[0] * silu(g0), y1 = o[1] * rs * sg[1] * silu(g1), y2 = o[2] * rs * sg[2] * silu(g2), y3 = o[3] * rs * sg[3] * silu(g3);
;     uint2 pk = {cvtpk(y0, y1), cvtpk(y2, y3)};
;     *(uint2*)(mixed + (size_t)tok * 4096 + 2048 + h * 256 + lane * 4) = pk;
.Ldc_loop1:
	v_add_u32_e32 v31, s28, v254
	v_cmp_gt_i32_e64 s[2:3], s23, v31
	s_and_saveexec_b64 s[18:19], s[2:3]
	s_cbranch_execz .Ldc_hskip1
	v_ashrrev_i32_e32 v248, 3, v31
	v_ashrrev_i32_e32 v249, 31, v248
	v_mov_b64_e32 v[252:253], s[42:43]
	v_lshlrev_b64 v[250:251], 13, v[248:249]
	v_mad_i64_i32 v[248:249], s[36:37], v248, s38, v[252:253]
	v_mov_b32_e32 v11, v7
	v_lshl_add_u64 v[248:249], v[248:249], 0, v[10:11]
	v_lshl_add_u64 v[248:249], v[4:5], 1, v[248:249]
	v_lshl_add_u64 v[250:251], v[12:13], 0, v[250:251]
	v_add_co_u32_e32 v252, vcc, 0x4000, v248
	s_nop 1
	v_addc_co_u32_e32 v253, vcc, 0, v249, vcc
	global_load_dwordx2 v[22:23], v[250:251], off
	global_load_dwordx2 v[18:19], v[250:251], off offset:512
	s_nop 0
	global_load_dwordx2 v[20:21], v[252:253], off offset:3200
.Ldc_hskip1:
	s_or_b64 exec, exec, s[18:19]
	v_ashrrev_i32_e32 v32, 3, v14
	v_lshlrev_b32_e32 v0, 16, v26
	v_lshlrev_b32_e32 v2, 16, v24
	v_fma_f32 v0, -v30, v2, v0
	v_and_b32_e32 v2, 0xffff0000, v26
	v_and_b32_e32 v6, 0xffff0000, v24
	v_fma_f32 v2, -v30, v6, v2
	v_lshlrev_b32_e32 v6, 16, v27
	v_lshlrev_b32_e32 v11, 16, v25
	v_fma_f32 v6, -v30, v11, v6
	v_and_b32_e32 v11, 0xffff0000, v27
	v_and_b32_e32 v14, 0xffff0000, v25
	v_fma_f32 v11, -v30, v14, v11
	v_mul_f32_e32 v14, v2, v2
	v_fmac_f32_e32 v14, v0, v0
	v_fmac_f32_e32 v14, v6, v6
	v_fmac_f32_e32 v14, v11, v11
	v_lshlrev_b32_e32 v24, 16, v8
	v_and_b32_e32 v8, 0xffff0000, v8
	v_add_f32_dpp v14, v14, v14 quad_perm:[1,0,3,2] row_mask:0xf bank_mask:0xf bound_ctrl:1
	v_lshlrev_b32_e32 v26, 16, v9
	v_and_b32_e32 v34, 0xffff0000, v9
	v_add_f32_dpp v14, v14, v14 quad_perm:[2,3,0,1] row_mask:0xf bank_mask:0xf bound_ctrl:1
	v_mul_f32_e32 v9, 0xbfb8aa3b, v8
	v_exp_f32_e32 v9, v9
	v_add_f32_dpp v14, v14, v14 row_half_mirror row_mask:0xf bank_mask:0xf bound_ctrl:1
	s_nop 1
	v_add_f32_dpp v14, v14, v14 row_mirror row_mask:0xf bank_mask:0xf bound_ctrl:1
	v_mov_b32_e32 v16, v14
	s_nop 1
	v_permlane16_swap_b32_e32 v14, v16
	v_add_f32_e32 v14, v14, v16
	v_mov_b32_e32 v16, v14
	s_nop 1
	v_permlane32_swap_b32_e32 v14, v16
	v_add_f32_e32 v14, v14, v16
	v_fmamk_f32 v14, v14, 0x3b800000, v28
	v_mul_f32_e32 v16, 0x4b800000, v14
	v_cmp_gt_f32_e32 vcc, s39, v14
	s_nop 1
	v_cndmask_b32_e32 v14, v14, v16, vcc
	v_rsq_f32_e32 v14, v14
	s_nop 0
	v_mul_f32_e32 v16, 0x45800000, v14
	v_cndmask_b32_e32 v14, v14, v16, vcc
	v_mul_f32_e32 v33, 0x3f4ccccd, v14
	v_mul_f32_e32 v25, v0, v33
	v_add_f32_e32 v0, 1.0, v9
	v_rcp_f32_e32 v0, v0
	v_mul_f32_e32 v14, 0xbfb8aa3b, v24
	v_mul_f32_e32 v9, v2, v33
	v_exp_f32_e32 v14, v14
	v_pk_mul_f32 v[8:9], v[0:1], v[8:9]
	v_mul_f32_e32 v0, 0xbfb8aa3b, v26
	v_exp_f32_e32 v0, v0
	v_mul_f32_e32 v2, 0xbfb8aa3b, v34
	v_exp_f32_e32 v2, v2
	v_add_f32_e32 v14, 1.0, v14
	v_rcp_f32_e32 v14, v14
	v_add_f32_e32 v0, 1.0, v0
	v_rcp_f32_e32 v16, v0
	v_add_f32_e32 v0, 1.0, v2
	v_rcp_f32_e32 v2, v0
	v_pk_mul_f32 v[24:25], v[14:15], v[24:25]
	v_mul_f32_e32 v27, v6, v33
	v_mul_f32_e32 v14, v24, v25
	v_mul_f32_e32 v24, v8, v9
	v_pk_mul_f32 v[8:9], v[16:17], v[26:27]
	v_mul_f32_e32 v35, v11, v33
	v_mul_f32_e32 v0, v8, v9
	v_pk_mul_f32 v[8:9], v[2:3], v[34:35]
	v_ashrrev_i32_e32 v33, 31, v32
	v_mul_f32_e32 v2, v8, v9
	v_cvt_pk_bf16_f32 v8, v14, v24
	v_cvt_pk_bf16_f32 v9, v0, v2
	v_lshlrev_b64 v[24:25], 13, v[32:33]
	v_and_b32_e32 v0, 0x700, v29
	v_lshl_add_u64 v[24:25], s[44:45], 0, v[24:25]
	v_lshlrev_b32_e32 v6, 1, v0
	v_lshl_add_u64 v[24:25], v[24:25], 0, v[6:7]
	v_lshl_add_u64 v[24:25], v[4:5], 1, v[24:25]
	v_add_co_u32_e32 v24, vcc, 0x2b401000, v24
	v_add_u32_e32 v29, s22, v29
	s_nop 0
	v_addc_co_u32_e32 v25, vcc, 0, v25, vcc
	global_store_dwordx2 v[24:25], v[8:9], off
	v_mov_b32_e32 v14, v254
	v_mov_b32_e32 v254, v31
	v_cmp_lt_i32_e32 vcc, s33, v14
	s_cbranch_vccnz .LBB0_1480
	s_cmp_eq_u64 s[2:3], 0
	s_cbranch_scc1 .Ldc_w01
	s_waitcnt vmcnt(4)
	s_branch .Ldc_wd1

; __device__ __forceinline__ void diff_combine(const Params& p) {
;     ...
;   for (int u = gw; u < T_TOK * 8; u += nw) {
;     const int tok = u >> 3, h = u & 7;
;     const uint2 a = na, b = nb_, gq = ng;
;     const int un = u + nw;
;     if (un < T_TOK * 8) {
;       const int tokn = un >> 3, hn = un & 7;
;       const u16* o0 = ob + (size_t)tokn * 4096 + (hn * 2) * 256 + lane * 4;
;       na = *(const uint2*)o0; nb_ = *(const uint2*)(o0 + 256);
;       ng = *(const uint2*)(proj + (size_t)tokn * NEP + E_GB + hn * 256 + lane * 4);
;     }
.Ldc_wd1:
	v_mov_b64_e32 v[8:9], v[246:247]
	v_mov_b64_e32 v[24:25], v[244:245]
	v_mov_b64_e32 v[26:27], v[242:243]
.Ldc_loop2:
	v_add_u32_e32 v31, s28, v254
	v_cmp_gt_i32_e64 s[2:3], s23, v31
	s_and_saveexec_b64 s[18:19], s[2:3]
	s_cbranch_execz .Ldc_hskip2
	v_ashrrev_i32_e32 v248, 3, v31
	v_ashrrev_i32_e32 v249, 31, v248
	v_mov_b64_e32 v[252:253], s[42:43]
	v_lshlrev_b64 v[250:251], 13, v[248:249]
	v_mad_i64_i32 v[248:249], s[36:37], v248, s38, v[252:253]
	v_mov_b32_e32 v11, v7
	v_lshl_add_u64 v[248:249], v[248:249], 0, v[10:11]
	v_lshl_add_u64 v[248:249], v[4:5], 1, v[248:249]
	v_lshl_add_u64 v[250:251], v[12:13], 0, v[250:251]
	v_add_co_u32_e32 v252, vcc, 0x4000, v248
	s_nop 1
	v_addc_co_u32_e32 v253, vcc, 0, v249, vcc
	global_load_dwordx2 v[242:243], v[250:251], off
	global_load_dwordx2 v[244:245], v[250:251], off offset:512
	s_nop 0
	global_load_dwordx2 v[246:247], v[252:253], off offset:3200

; __device__ __forceinline__ void diff_combine(const Params& p) {
;     ...
;   for (int u = gw; u < T_TOK * 8; u += nw) {
;     const int tok = u >> 3, h = u & 7;
;     const uint2 a = na, b = nb_, gq = ng;
;     const int un = u + nw;
;     if (un < T_TOK * 8) {
;       const int tokn = un >> 3, hn = un & 7;
;       const u16* o0 = ob + (size_t)tokn * 4096 + (hn * 2) * 256 + lane * 4;
;       na = *(const uint2*)o0; nb_ = *(const uint2*)(o0 + 256);
;       ng = *(const uint2*)(proj + (size_t)tokn * NEP + E_GB + hn * 256 + lane * 4);
;     }
.Ldc_wd2:
	v_mov_b64_e32 v[8:9], v[20:21]
	v_mov_b64_e32 v[24:25], v[18:19]
	v_mov_b64_e32 v[26:27], v[22:23]
	s_branch .Ldc_loop1

; __device__ __forceinline__ void diff_combine(const Params& p) {
;     ...
;   for (int u = gw; u < T_TOK * 8; u += nw) {
;     const int tok = u >> 3, h = u & 7;
;     const uint2 a = na, b = nb_, gq = ng;
;     const int un = u + nw;
;     if (un < T_TOK * 8) {
;       const int tokn = un >> 3, hn = un & 7;
;       const u16* o0 = ob + (size_t)tokn * 4096 + (hn * 2) * 256 + lane * 4;
;       na = *(const uint2*)o0; nb_ = *(const uint2*)(o0 + 256);
;       ng = *(const uint2*)(proj + (size_t)tokn * NEP + E_GB + hn * 256 + lane * 4);
;     }
	.amdhsa_kernel _Z14fwd_megakernel6Params
		.amdhsa_group_segment_fixed_size 16
		.amdhsa_private_segment_fixed_size 0
		.amdhsa_kernarg_size 392
		.amdhsa_user_sgpr_count 2
		.amdhsa_user_sgpr_dispatch_ptr 0
		.amdhsa_user_sgpr_queue_ptr 0
		.amdhsa_user_sgpr_kernarg_segment_ptr 1
		.amdhsa_user_sgpr_dispatch_id 0
		.amdhsa_user_sgpr_kernarg_preload_length 0
		.amdhsa_user_sgpr_kernarg_preload_offset 0
		.amdhsa_user_sgpr_private_segment_size 0
		.amdhsa_uses_dynamic_stack 0
		.amdhsa_enable_private_segment 0
		.amdhsa_system_sgpr_workgroup_id_x 1
		.amdhsa_system_sgpr_workgroup_id_y 0
		.amdhsa_system_sgpr_workgroup_id_z 0
		.amdhsa_system_sgpr_workgroup_info 0
		.amdhsa_system_vgpr_workitem_id 2
		.amdhsa_next_free_vgpr 256
		.amdhsa_next_free_sgpr 98
		.amdhsa_accum_offset 256
		.amdhsa_reserve_vcc 1
		.amdhsa_float_round_mode_32 0
		.amdhsa_float_round_mode_16_64 0
		.amdhsa_float_denorm_mode_32 3
		.amdhsa_float_denorm_mode_16_64 3
		.amdhsa_dx10_clamp 1
		.amdhsa_ieee_mode 1
		.amdhsa_fp16_overflow 0
		.amdhsa_tg_split 0
		.amdhsa_exception_fp_ieee_invalid_op 0
		.amdhsa_exception_fp_denorm_src 0
		.amdhsa_exception_fp_ieee_div_zero 0
		.amdhsa_exception_fp_ieee_overflow 0
		.amdhsa_exception_fp_ieee_underflow 0
		.amdhsa_exception_fp_ieee_inexact 0
		.amdhsa_exception_int_div_zero 0
	.end_amdhsa_kernel

; __device__ __forceinline__ void diff_combine(const Params& p) {
;     ...
;   for (int u = gw; u < T_TOK * 8; u += nw) {
;     const int tok = u >> 3, h = u & 7;
;     const uint2 a = na, b = nb_, gq = ng;
;     const int un = u + nw;
;     if (un < T_TOK * 8) {
;       const int tokn = un >> 3, hn = un & 7;
;       const u16* o0 = ob + (size_t)tokn * 4096 + (hn * 2) * 256 + lane * 4;
;       na = *(const uint2*)o0; nb_ = *(const uint2*)(o0 + 256);
;       ng = *(const uint2*)(proj + (size_t)tokn * NEP + E_GB + hn * 256 + lane * 4);
;     }
amdhsa.kernels:
  - .agpr_count:     0
    .args:
      - .offset:         0
        .size:           136
        .value_kind:     by_value
      - .offset:         136
        .size:           4
        .value_kind:     hidden_block_count_x
      - .offset:         140
        .size:           4
        .value_kind:     hidden_block_count_y
      - .offset:         144
        .size:           4
        .value_kind:     hidden_block_count_z
      - .offset:         148
        .size:           2
        .value_kind:     hidden_group_size_x
      - .offset:         150
        .size:           2
        .value_kind:     hidden_group_size_y
      - .offset:         152
        .size:           2
        .value_kind:     hidden_group_size_z
      - .offset:         154
        .size:           2
        .value_kind:     hidden_remainder_x
      - .offset:         156
        .size:           2
        .value_kind:     hidden_remainder_y
      - .offset:         158
        .size:           2
        .value_kind:     hidden_remainder_z
      - .offset:         176
        .size:           8
        .value_kind:     hidden_global_offset_x
      - .offset:         184
        .size:           8
        .value_kind:     hidden_global_offset_y
      - .offset:         192
        .size:           8
        .value_kind:     hidden_global_offset_z
      - .offset:         200
        .size:           2
        .value_kind:     hidden_grid_dims
      - .offset:         224
        .size:           8
        .value_kind:     hidden_multigrid_sync_arg
      - .offset:         256
        .size:           4
        .value_kind:     hidden_dynamic_lds_size
    .group_segment_fixed_size: 16
    .kernarg_segment_align: 8
    .kernarg_segment_size: 392
    .language:       OpenCL C
    .language_version:
      - 2
      - 0
    .max_flat_workgroup_size: 512
    .name:           _Z14fwd_megakernel6Params
    .private_segment_fixed_size: 0
    .sgpr_count:     104
    .sgpr_spill_count: 130
    .symbol:         _Z14fwd_megakernel6Params.kd
    .uniform_work_group_size: 1
    .uses_dynamic_stack: false
    .vgpr_count:     256
    .vgpr_spill_count: 0
    .wavefront_size: 64
